# v66 plus exact counted vmcnt waits in the scan staging (was vmcnt(5)/vmcnt(0))
# baseline (speedup 1.0000x reference)
.LBB0_986:
	s_waitcnt vmcnt(17)
	v_cvt_f32_u32_sdwa v88, v148 dst_sel:DWORD dst_unused:UNUSED_PAD src0_sel:WORD_0
	v_cvt_f32_u32_sdwa v89, v148 dst_sel:DWORD dst_unused:UNUSED_PAD src0_sel:WORD_1
	v_cvt_f32_u32_sdwa v90, v149 dst_sel:DWORD dst_unused:UNUSED_PAD src0_sel:WORD_0
	v_cvt_f32_u32_sdwa v91, v149 dst_sel:DWORD dst_unused:UNUSED_PAD src0_sel:WORD_1
	v_lshlrev_b32_e32 v80, 16, v142
	v_and_b32_e32 v81, 0xffff0000, v142
	v_lshlrev_b32_e32 v82, 16, v143
	v_and_b32_e32 v83, 0xffff0000, v143
	v_pk_mul_f32 v[84:85], v[2:3], v[82:83]
	v_pk_mul_f32 v[86:87], v[0:1], v[80:81]
	v_pk_mul_f32 v[92:93], v[84:85], v[84:85]
	v_pk_mul_f32 v[94:95], v[86:87], v[86:87]
	v_lshlrev_b32_e32 v76, 16, v140
	v_pk_mov_b32 v[96:97], v[94:95], v[92:93] op_sel:[1,0]
	v_mov_b32_e32 v95, v93
	v_pk_add_f32 v[92:93], v[96:97], v[94:95]
	v_pk_fma_f32 v[94:95], v[90:91], s[54:55], -1.0 op_sel_hi:[1,0,0]
	v_pk_fma_f32 v[96:97], v[88:89], s[54:55], -1.0 op_sel_hi:[1,0,0]
	v_pk_fma_f32 v[94:95], v[6:7], v[94:95], 1.0 op_sel_hi:[1,1,0]
	v_pk_fma_f32 v[96:97], v[4:5], v[96:97], 1.0 op_sel_hi:[1,1,0]
	v_and_b32_e32 v77, 0xffff0000, v140
	v_lshlrev_b32_e32 v78, 16, v141
	v_and_b32_e32 v79, 0xffff0000, v141
	v_pk_mul_f32 v[82:83], v[94:95], v[82:83]
	v_pk_mul_f32 v[80:81], v[96:97], v[80:81]
	v_pk_mul_f32 v[96:97], v[82:83], v[78:79]
	v_pk_mul_f32 v[94:95], v[80:81], v[76:77]
	v_pk_mul_f32 v[96:97], v[10:11], v[96:97]
	v_pk_mul_f32 v[94:95], v[8:9], v[94:95]
	v_add_f32_e32 v92, v92, v93
	v_add_f32_e32 v94, v94, v95
	v_add_f32_e32 v95, v96, v97
	v_add_f32_e32 v94, v94, v95
	v_add_f32_dpp v92, v92, v92 quad_perm:[1,0,3,2] row_mask:0xf bank_mask:0xf bound_ctrl:1
	s_nop 0
	v_add_f32_dpp v94, v94, v94 quad_perm:[1,0,3,2] row_mask:0xf bank_mask:0xf bound_ctrl:1
	v_add_f32_dpp v92, v92, v92 quad_perm:[2,3,0,1] row_mask:0xf bank_mask:0xf bound_ctrl:1
	s_nop 0
	v_add_f32_dpp v94, v94, v94 quad_perm:[2,3,0,1] row_mask:0xf bank_mask:0xf bound_ctrl:1
	v_add_f32_dpp v92, v92, v92 row_half_mirror row_mask:0xf bank_mask:0xf bound_ctrl:1
	s_nop 0
	v_add_f32_dpp v94, v94, v94 row_half_mirror row_mask:0xf bank_mask:0xf bound_ctrl:1
	v_mov_b32_dpp v93, v92 row_mirror row_mask:0xf bank_mask:0xf bound_ctrl:1
	s_nop 0
	v_mov_b32_dpp v95, v94 row_mirror row_mask:0xf bank_mask:0xf bound_ctrl:1
	s_and_saveexec_b64 s[12:13], s[4:5]
	s_cbranch_execz .LBB0_988
	v_lshlrev_b64 v[96:97], 7, v[134:135]
	v_lshl_add_u64 v[96:97], s[48:49], 0, v[96:97]
	v_add_f32_e32 v94, v94, v95
	global_store_dword v[96:97], v94, off

.LBB0_999:
	s_waitcnt vmcnt(12)
	v_cvt_f32_u32_sdwa v88, v160 dst_sel:DWORD dst_unused:UNUSED_PAD src0_sel:WORD_0
	v_cvt_f32_u32_sdwa v89, v160 dst_sel:DWORD dst_unused:UNUSED_PAD src0_sel:WORD_1
	v_cvt_f32_u32_sdwa v90, v161 dst_sel:DWORD dst_unused:UNUSED_PAD src0_sel:WORD_0
	v_cvt_f32_u32_sdwa v91, v161 dst_sel:DWORD dst_unused:UNUSED_PAD src0_sel:WORD_1
	v_lshlrev_b32_e32 v80, 16, v156
	v_and_b32_e32 v81, 0xffff0000, v156
	v_lshlrev_b32_e32 v82, 16, v157
	v_and_b32_e32 v83, 0xffff0000, v157
	v_pk_mul_f32 v[84:85], v[2:3], v[82:83]
	v_pk_mul_f32 v[86:87], v[0:1], v[80:81]
	v_pk_mul_f32 v[92:93], v[84:85], v[84:85]
	v_pk_mul_f32 v[94:95], v[86:87], v[86:87]
	v_lshlrev_b32_e32 v76, 16, v158
	v_pk_mov_b32 v[96:97], v[94:95], v[92:93] op_sel:[1,0]
	v_mov_b32_e32 v95, v93
	v_pk_add_f32 v[92:93], v[96:97], v[94:95]
	v_pk_fma_f32 v[94:95], v[90:91], s[54:55], -1.0 op_sel_hi:[1,0,0]
	v_pk_fma_f32 v[96:97], v[88:89], s[54:55], -1.0 op_sel_hi:[1,0,0]
	v_pk_fma_f32 v[94:95], v[6:7], v[94:95], 1.0 op_sel_hi:[1,1,0]
	v_pk_fma_f32 v[96:97], v[4:5], v[96:97], 1.0 op_sel_hi:[1,1,0]
	v_and_b32_e32 v77, 0xffff0000, v158
	v_lshlrev_b32_e32 v78, 16, v159
	v_and_b32_e32 v79, 0xffff0000, v159
	v_pk_mul_f32 v[82:83], v[94:95], v[82:83]
	v_pk_mul_f32 v[80:81], v[96:97], v[80:81]
	v_pk_mul_f32 v[96:97], v[82:83], v[78:79]
	v_pk_mul_f32 v[94:95], v[80:81], v[76:77]
	v_pk_mul_f32 v[96:97], v[10:11], v[96:97]
	v_pk_mul_f32 v[94:95], v[8:9], v[94:95]
	v_add_f32_e32 v92, v92, v93
	v_add_f32_e32 v94, v94, v95
	v_add_f32_e32 v95, v96, v97
	v_add_f32_e32 v94, v94, v95
	v_add_f32_dpp v92, v92, v92 quad_perm:[1,0,3,2] row_mask:0xf bank_mask:0xf bound_ctrl:1
	s_nop 0
	v_add_f32_dpp v94, v94, v94 quad_perm:[1,0,3,2] row_mask:0xf bank_mask:0xf bound_ctrl:1
	v_add_f32_dpp v92, v92, v92 quad_perm:[2,3,0,1] row_mask:0xf bank_mask:0xf bound_ctrl:1
	s_nop 0
	v_add_f32_dpp v94, v94, v94 quad_perm:[2,3,0,1] row_mask:0xf bank_mask:0xf bound_ctrl:1
	v_add_f32_dpp v92, v92, v92 row_half_mirror row_mask:0xf bank_mask:0xf bound_ctrl:1
	s_nop 0
	v_add_f32_dpp v94, v94, v94 row_half_mirror row_mask:0xf bank_mask:0xf bound_ctrl:1
	v_mov_b32_dpp v93, v92 row_mirror row_mask:0xf bank_mask:0xf bound_ctrl:1
	s_nop 0
	v_mov_b32_dpp v95, v94 row_mirror row_mask:0xf bank_mask:0xf bound_ctrl:1
	s_and_saveexec_b64 s[14:15], s[4:5]
	s_cbranch_execz .LBB0_1001
	v_lshlrev_b64 v[96:97], 7, v[154:155]
	v_lshl_add_u64 v[96:97], s[48:49], 0, v[96:97]
	v_add_f32_e32 v94, v94, v95
	global_store_dword v[96:97], v94, off

.LBB0_1039:
	s_waitcnt vmcnt(17)
	v_cvt_f32_u32_sdwa v56, v128 dst_sel:DWORD dst_unused:UNUSED_PAD src0_sel:WORD_0
	v_cvt_f32_u32_sdwa v57, v128 dst_sel:DWORD dst_unused:UNUSED_PAD src0_sel:WORD_1
	v_cvt_f32_u32_sdwa v58, v129 dst_sel:DWORD dst_unused:UNUSED_PAD src0_sel:WORD_0
	v_cvt_f32_u32_sdwa v59, v129 dst_sel:DWORD dst_unused:UNUSED_PAD src0_sel:WORD_1
	v_lshlrev_b32_e32 v48, 16, v110
	v_and_b32_e32 v49, 0xffff0000, v110
	v_lshlrev_b32_e32 v50, 16, v111
	v_and_b32_e32 v51, 0xffff0000, v111
	v_pk_mul_f32 v[52:53], v[2:3], v[50:51]
	v_pk_mul_f32 v[54:55], v[0:1], v[48:49]
	v_pk_mul_f32 v[60:61], v[52:53], v[52:53]
	v_pk_mul_f32 v[62:63], v[54:55], v[54:55]
	v_lshlrev_b32_e32 v44, 16, v108
	v_pk_mov_b32 v[64:65], v[62:63], v[60:61] op_sel:[1,0]
	v_mov_b32_e32 v63, v61
	v_pk_add_f32 v[60:61], v[64:65], v[62:63]
	v_pk_fma_f32 v[62:63], v[58:59], s[54:55], -1.0 op_sel_hi:[1,0,0]
	v_pk_fma_f32 v[64:65], v[56:57], s[54:55], -1.0 op_sel_hi:[1,0,0]
	v_pk_fma_f32 v[62:63], v[6:7], v[62:63], 1.0 op_sel_hi:[1,1,0]
	v_pk_fma_f32 v[64:65], v[4:5], v[64:65], 1.0 op_sel_hi:[1,1,0]
	v_and_b32_e32 v45, 0xffff0000, v108
	v_lshlrev_b32_e32 v46, 16, v109
	v_and_b32_e32 v47, 0xffff0000, v109
	v_pk_mul_f32 v[50:51], v[62:63], v[50:51]
	v_pk_mul_f32 v[48:49], v[64:65], v[48:49]
	v_pk_mul_f32 v[64:65], v[50:51], v[46:47]
	v_pk_mul_f32 v[62:63], v[48:49], v[44:45]
	v_pk_mul_f32 v[64:65], v[10:11], v[64:65]
	v_pk_mul_f32 v[62:63], v[8:9], v[62:63]
	v_add_f32_e32 v60, v60, v61
	v_add_f32_e32 v62, v62, v63
	v_add_f32_e32 v63, v64, v65
	v_add_f32_e32 v62, v62, v63
	v_add_f32_dpp v60, v60, v60 quad_perm:[1,0,3,2] row_mask:0xf bank_mask:0xf bound_ctrl:1
	s_nop 0
	v_add_f32_dpp v62, v62, v62 quad_perm:[1,0,3,2] row_mask:0xf bank_mask:0xf bound_ctrl:1
	v_add_f32_dpp v60, v60, v60 quad_perm:[2,3,0,1] row_mask:0xf bank_mask:0xf bound_ctrl:1
	s_nop 0
	v_add_f32_dpp v62, v62, v62 quad_perm:[2,3,0,1] row_mask:0xf bank_mask:0xf bound_ctrl:1
	v_add_f32_dpp v60, v60, v60 row_half_mirror row_mask:0xf bank_mask:0xf bound_ctrl:1
	s_nop 0
	v_add_f32_dpp v62, v62, v62 row_half_mirror row_mask:0xf bank_mask:0xf bound_ctrl:1
	v_mov_b32_dpp v61, v60 row_mirror row_mask:0xf bank_mask:0xf bound_ctrl:1
	s_nop 0
	v_mov_b32_dpp v63, v62 row_mirror row_mask:0xf bank_mask:0xf bound_ctrl:1
	s_and_saveexec_b64 s[12:13], s[8:9]
	s_cbranch_execz .LBB0_1041
	v_lshlrev_b64 v[64:65], 7, v[102:103]
	v_lshl_add_u64 v[64:65], s[36:37], 0, v[64:65]
	v_add_f32_e32 v62, v62, v63
	global_store_dword v[64:65], v62, off

.LBB0_1052:
	s_waitcnt vmcnt(12)
	v_cvt_f32_u32_sdwa v56, v140 dst_sel:DWORD dst_unused:UNUSED_PAD src0_sel:WORD_0
	v_cvt_f32_u32_sdwa v57, v140 dst_sel:DWORD dst_unused:UNUSED_PAD src0_sel:WORD_1
	v_cvt_f32_u32_sdwa v58, v141 dst_sel:DWORD dst_unused:UNUSED_PAD src0_sel:WORD_0
	v_cvt_f32_u32_sdwa v59, v141 dst_sel:DWORD dst_unused:UNUSED_PAD src0_sel:WORD_1
	v_lshlrev_b32_e32 v48, 16, v136
	v_and_b32_e32 v49, 0xffff0000, v136
	v_lshlrev_b32_e32 v50, 16, v137
	v_and_b32_e32 v51, 0xffff0000, v137
	v_pk_mul_f32 v[52:53], v[2:3], v[50:51]
	v_pk_mul_f32 v[54:55], v[0:1], v[48:49]
	v_pk_mul_f32 v[60:61], v[52:53], v[52:53]
	v_pk_mul_f32 v[62:63], v[54:55], v[54:55]
	v_lshlrev_b32_e32 v44, 16, v138
	v_pk_mov_b32 v[64:65], v[62:63], v[60:61] op_sel:[1,0]
	v_mov_b32_e32 v63, v61
	v_pk_add_f32 v[60:61], v[64:65], v[62:63]
	v_pk_fma_f32 v[62:63], v[58:59], s[54:55], -1.0 op_sel_hi:[1,0,0]
	v_pk_fma_f32 v[64:65], v[56:57], s[54:55], -1.0 op_sel_hi:[1,0,0]
	v_pk_fma_f32 v[62:63], v[6:7], v[62:63], 1.0 op_sel_hi:[1,1,0]
	v_pk_fma_f32 v[64:65], v[4:5], v[64:65], 1.0 op_sel_hi:[1,1,0]
	v_and_b32_e32 v45, 0xffff0000, v138
	v_lshlrev_b32_e32 v46, 16, v139
	v_and_b32_e32 v47, 0xffff0000, v139
	v_pk_mul_f32 v[50:51], v[62:63], v[50:51]
	v_pk_mul_f32 v[48:49], v[64:65], v[48:49]
	v_pk_mul_f32 v[64:65], v[50:51], v[46:47]
	v_pk_mul_f32 v[62:63], v[48:49], v[44:45]
	v_pk_mul_f32 v[64:65], v[10:11], v[64:65]
	v_pk_mul_f32 v[62:63], v[8:9], v[62:63]
	v_add_f32_e32 v60, v60, v61
	v_add_f32_e32 v62, v62, v63
	v_add_f32_e32 v63, v64, v65
	v_add_f32_e32 v62, v62, v63
	v_add_f32_dpp v60, v60, v60 quad_perm:[1,0,3,2] row_mask:0xf bank_mask:0xf bound_ctrl:1
	s_nop 0
	v_add_f32_dpp v62, v62, v62 quad_perm:[1,0,3,2] row_mask:0xf bank_mask:0xf bound_ctrl:1
	v_add_f32_dpp v60, v60, v60 quad_perm:[2,3,0,1] row_mask:0xf bank_mask:0xf bound_ctrl:1
	s_nop 0
	v_add_f32_dpp v62, v62, v62 quad_perm:[2,3,0,1] row_mask:0xf bank_mask:0xf bound_ctrl:1
	v_add_f32_dpp v60, v60, v60 row_half_mirror row_mask:0xf bank_mask:0xf bound_ctrl:1
	s_nop 0
	v_add_f32_dpp v62, v62, v62 row_half_mirror row_mask:0xf bank_mask:0xf bound_ctrl:1
	v_mov_b32_dpp v61, v60 row_mirror row_mask:0xf bank_mask:0xf bound_ctrl:1
	s_nop 0
	v_mov_b32_dpp v63, v62 row_mirror row_mask:0xf bank_mask:0xf bound_ctrl:1
	s_and_saveexec_b64 s[14:15], s[8:9]
	s_cbranch_execz .LBB0_1054
	v_lshlrev_b64 v[64:65], 7, v[134:135]
	v_lshl_add_u64 v[64:65], s[36:37], 0, v[64:65]
	v_add_f32_e32 v62, v62, v63
	global_store_dword v[64:65], v62, off
